# E51b: layer-1 memory-attention PROMPT units (the 256-unit variant): K/V prefetch distance 1->2 tiles, two landing sets by parity, vmcnt(4) stage-in wait; on E41
# baseline (speedup 1.0000x reference)
.LBB0_1317:
	s_and_b64 vcc, exec, s[20:21]
	s_cbranch_vccz .LBB0_1331
	s_getreg_b32 s6, hwreg(HW_REG_HW_ID, 0, 6)
	s_and_b32 s6, s6, 63
	s_lshl_b32 s6, s6, 2
	s_add_i32 s6, s6, 0
	s_add_i32 s8, s6, 0x23e00
	s_mov_b64 s[6:7], src_shared_base
	v_mov_b32_e32 v4, s8
	v_mov_b32_e32 v5, s7
	flat_load_dword v2, v[4:5] sc0 sc1
	s_waitcnt vmcnt(0)
	s_add_i32 s7, s3, -1
	v_mov_b32_e32 v153, v3
	v_mov_b32_e32 v158, 0xf149f2ca
	s_waitcnt lgkmcnt(0)
	v_readfirstlane_b32 s6, v2
	s_nop 1
	v_lshl_add_u32 v28, s6, 6, v217
	v_ashrrev_i32_e32 v2, 31, v28
	v_readfirstlane_b32 s6, v28
	s_ashr_i32 s6, s6, 1
	s_andn2_b32 s6, s6, 31
	v_add_u32_e32 v12, 0x200, v28
	v_or_b32_e32 v156, s6, v212
	v_lshrrev_b32_e32 v2, 28, v2
	v_ashrrev_i32_e32 v13, 31, v12
	v_min_i32_e32 v4, s7, v156
	v_add_u32_e32 v2, v28, v2
	v_lshrrev_b32_e32 v13, 28, v13
	v_ashrrev_i32_e32 v5, 31, v4
	v_ashrrev_i32_e32 v20, 4, v2
	v_and_b32_e32 v2, -16, v2
	v_add_u32_e32 v13, v12, v13
	v_lshlrev_b64 v[4:5], 10, v[4:5]
	v_sub_u32_e32 v2, v28, v2
	v_ashrrev_i32_e32 v24, 4, v13
	v_and_b32_e32 v13, -16, v13
	v_lshl_add_u64 v[4:5], s[34:35], 0, v[4:5]
	v_lshlrev_b32_e32 v22, 3, v2
	v_sub_u32_e32 v29, v12, v13
	v_lshl_add_u64 v[4:5], v[4:5], 0, v[152:153]
	v_ashrrev_i32_e32 v23, 31, v22
	v_lshlrev_b32_e32 v26, 3, v29
	global_load_dwordx4 v[142:145], v[4:5], off
	global_load_dwordx4 v[138:141], v[4:5], off offset:32
	global_load_dwordx4 v[134:137], v[4:5], off offset:64
	global_load_dwordx4 v[130:133], v[4:5], off offset:96
	global_load_dwordx4 v[126:129], v[4:5], off offset:128
	global_load_dwordx4 v[122:125], v[4:5], off offset:160
	global_load_dwordx4 v[118:121], v[4:5], off offset:192
	global_load_dwordx4 v[114:117], v[4:5], off offset:224
	v_mad_i64_i32 v[4:5], s[8:9], s30, v20, v[22:23]
	v_ashrrev_i32_e32 v27, 31, v26
	v_lshlrev_b64 v[8:9], 1, v[4:5]
	v_mad_i64_i32 v[12:13], s[8:9], s30, v24, v[26:27]
	v_lshl_add_u64 v[4:5], s[26:27], 0, v[8:9]
	v_lshlrev_b64 v[16:17], 1, v[12:13]
	global_load_dwordx4 v[4:7], v[4:5], off
	v_lshl_add_u64 v[8:9], s[28:29], 0, v[8:9]
	v_lshl_add_u64 v[12:13], s[26:27], 0, v[16:17]
	global_load_dwordx4 v[8:11], v[8:9], off
	v_lshl_add_u64 v[16:17], s[28:29], 0, v[16:17]
	global_load_dwordx4 v[12:15], v[12:13], off
	v_mul_lo_u32 v171, v20, s71
	global_load_dwordx4 v[16:19], v[16:17], off
	v_lshlrev_b32_e32 v172, 4, v2
	v_add3_u32 v2, 0, v171, v172
	v_mul_lo_u32 v174, v24, s71
	v_lshlrev_b32_e32 v175, 4, v29
	s_barrier
	v_ashrrev_i32_e32 v25, 31, v24
	s_cmp_lt_i32 s6, s3
	s_cselect_b64 s[20:21], -1, 0
	s_lshl_b32 s10, s30, 1
	v_ashrrev_i32_e32 v21, 31, v20
	v_mul_lo_u32 v173, v20, s70
	v_mul_lo_u32 v191, v24, s70
	v_mov_b32_e32 v153, 0
	s_waitcnt vmcnt(3)
	ds_write_b128 v2, v[4:7]
	v_mad_u64_u32 v[4:5], s[8:9], v20, 48, v[2:3]
	v_add3_u32 v2, 0, v174, v175
	s_waitcnt vmcnt(2)
	ds_write_b128 v4, v[8:11] offset:17408
	s_waitcnt vmcnt(1)
	ds_write_b128 v2, v[12:15]
	v_mad_u64_u32 v[4:5], s[8:9], v24, 48, v[2:3]
	v_lshrrev_b32_e32 v2, 2, v28
	s_waitcnt vmcnt(0)
	ds_write_b128 v4, v[16:19] offset:17408
	v_and_or_b32 v4, v2, 3, v216
	v_mul_u32_u24_e32 v170, 0x140, v4
	v_lshl_add_u64 v[4:5], v[24:25], 0, 64
	v_lshlrev_b64 v[6:7], 1, v[26:27]
	v_mad_u64_u32 v[6:7], s[6:7], s10, v4, v[6:7]
	v_mad_i32_i24 v7, s10, v5, v7
	v_lshl_add_u64 v[160:161], s[26:27], 0, v[6:7]
	v_lshl_add_u64 v[162:163], s[28:29], 0, v[6:7]
	v_lshl_add_u64 v[4:5], v[20:21], 0, 64
	v_lshlrev_b64 v[6:7], 1, v[22:23]
	v_mad_u64_u32 v[6:7], s[8:9], s10, v4, v[6:7]
	v_and_or_b32 v2, v2, 4, v225
	v_mad_i32_i24 v7, s10, v5, v7
	v_mov_b32_e32 v16, v3
	v_mov_b32_e32 v17, v3
	v_lshlrev_b32_e32 v157, 3, v2
	v_lshl_add_u64 v[164:165], s[26:27], 0, v[6:7]
	v_lshl_add_u64 v[166:167], s[28:29], 0, v[6:7]
	global_load_dwordx4 v[226:229], v[164:165], off
	global_load_dwordx4 v[230:233], v[166:167], off
	global_load_dwordx4 v[234:237], v[160:161], off
	global_load_dwordx4 v[238:241], v[162:163], off
	v_mov_b32_e32 v2, v3
	v_mov_b32_e32 v4, v3
	v_mov_b32_e32 v5, v3
	v_mov_b32_e32 v6, v3
	v_mov_b32_e32 v7, v3
	v_mov_b32_e32 v8, v3
	v_mov_b32_e32 v9, v3
	v_mov_b32_e32 v10, v3
	v_mov_b32_e32 v11, v3
	v_mov_b32_e32 v12, v3
	v_mov_b32_e32 v13, v3
	v_mov_b32_e32 v14, v3
	v_mov_b32_e32 v15, v3
	v_mov_b64_e32 v[32:33], v[16:17]
	v_mov_b64_e32 v[48:49], v[16:17]
	v_mov_b64_e32 v[64:65], v[16:17]
	v_mov_b64_e32 v[80:81], v[16:17]
	s_lshl_b32 s6, s30, 7
	s_mov_b32 s7, 0
	s_mov_b64 s[26:27], 0
	v_mov_b64_e32 v[30:31], v[14:15]
	v_mov_b64_e32 v[28:29], v[12:13]
	v_mov_b64_e32 v[26:27], v[10:11]
	v_mov_b64_e32 v[24:25], v[8:9]
	v_mov_b64_e32 v[22:23], v[6:7]
	v_mov_b64_e32 v[20:21], v[4:5]
	v_mov_b64_e32 v[18:19], v[2:3]
	v_mov_b64_e32 v[46:47], v[14:15]
	v_mov_b64_e32 v[44:45], v[12:13]
	v_mov_b64_e32 v[42:43], v[10:11]
	v_mov_b64_e32 v[40:41], v[8:9]
	v_mov_b64_e32 v[38:39], v[6:7]
	v_mov_b64_e32 v[36:37], v[4:5]
	v_mov_b64_e32 v[34:35], v[2:3]
	v_mov_b64_e32 v[62:63], v[14:15]
	v_mov_b64_e32 v[60:61], v[12:13]
	v_mov_b64_e32 v[58:59], v[10:11]
	v_mov_b64_e32 v[56:57], v[8:9]
	v_mov_b64_e32 v[54:55], v[6:7]
	v_mov_b64_e32 v[52:53], v[4:5]
	v_mov_b64_e32 v[50:51], v[2:3]
	v_mov_b64_e32 v[78:79], v[14:15]
	v_mov_b64_e32 v[76:77], v[12:13]
	v_mov_b64_e32 v[74:75], v[10:11]
	v_mov_b64_e32 v[72:73], v[8:9]
	v_mov_b64_e32 v[70:71], v[6:7]
	v_mov_b64_e32 v[68:69], v[4:5]
	v_mov_b64_e32 v[66:67], v[2:3]
	s_waitcnt lgkmcnt(0)
	s_barrier
	s_branch .LBB0_1321

.LBB0_1320:
	s_add_i32 s7, s7, 1
	s_bitcmp1_b32 s7, 0
	s_cselect_b32 s8, 0x9400, 0
	s_add_i32 s8, s8, 0
	s_add_u32 s26, s26, s6
	s_addc_u32 s27, s27, 0
	s_cmp_lt_u32 s7, 3
	s_cbranch_scc1 .LmdL1p_w4
	s_waitcnt vmcnt(0)
	s_branch .LmdL1p_wd

.LmdL1p_wd:
	s_bitcmp1_b32 s7, 0
	s_cbranch_scc1 .LmdL1p_wB
	v_add3_u32 v2, s8, v171, v172
	ds_write_b128 v2, v[4:7]
	v_add3_u32 v2, s8, v173, v172
	ds_write_b128 v2, v[8:11] offset:17408
	v_add3_u32 v2, s8, v174, v175
	ds_write_b128 v2, v[12:15]
	v_add3_u32 v2, s8, v191, v175
	ds_write_b128 v2, v[146:149] offset:17408
	s_branch .LmdL1p_wj
.LmdL1p_wB:
	v_add3_u32 v2, s8, v171, v172
	ds_write_b128 v2, v[226:229]
	v_add3_u32 v2, s8, v173, v172
	ds_write_b128 v2, v[230:233] offset:17408
	v_add3_u32 v2, s8, v174, v175
	ds_write_b128 v2, v[234:237]
	v_add3_u32 v2, s8, v191, v175
	ds_write_b128 v2, v[238:241] offset:17408
.LmdL1p_wj:
	s_cmp_eq_u32 s7, 3
	s_waitcnt lgkmcnt(0)
	s_barrier
	s_cbranch_scc1 .LBB0_1324
.LBB0_1321:
	s_cmp_gt_u32 s7, 1
	s_cbranch_scc1 .LmdL1p_nl
	s_add_u32 s98, s26, s6
	s_addc_u32 s99, s27, 0
	s_bitcmp1_b32 s7, 0
	s_cbranch_scc1 .LmdL1p_gB
	v_lshl_add_u64 v[242:243], v[164:165], 0, s[98:99]
	global_load_dwordx4 v[4:7], v[242:243], off
	v_lshl_add_u64 v[242:243], v[166:167], 0, s[98:99]
	global_load_dwordx4 v[8:11], v[242:243], off
	v_lshl_add_u64 v[242:243], v[160:161], 0, s[98:99]
	global_load_dwordx4 v[12:15], v[242:243], off
	v_lshl_add_u64 v[242:243], v[162:163], 0, s[98:99]
	global_load_dwordx4 v[146:149], v[242:243], off
	s_branch .LmdL1p_nl

.LmdL1p_nl:
	v_cndmask_b32_e64 v2, 0, 1, s[20:21]
	v_cmp_ne_u32_e64 s[18:19], 1, v2
	s_andn2_b64 vcc, exec, s[20:21]
	s_cbranch_vccnz .LBB0_1320
	s_bitcmp1_b32 s7, 0
	s_cselect_b32 s8, 0x9400, 0
	s_add_i32 s8, s8, 0
	v_add3_u32 v2, s8, v214, v159
	ds_read_b128 v[82:85], v2
	ds_read_b128 v[86:89], v2 offset:32
	s_waitcnt lgkmcnt(1)
	v_mfma_f32_32x32x16_bf16 v[98:113], v[82:85], v[142:145], 0
	s_waitcnt lgkmcnt(0)
	v_mfma_f32_32x32x16_bf16 v[98:113], v[86:89], v[138:141], v[98:113]
	ds_read_b128 v[82:85], v2 offset:64
	ds_read_b128 v[86:89], v2 offset:96
	s_waitcnt lgkmcnt(1)
	v_mfma_f32_32x32x16_bf16 v[98:113], v[82:85], v[134:137], v[98:113]
	s_waitcnt lgkmcnt(0)
	v_mfma_f32_32x32x16_bf16 v[98:113], v[86:89], v[130:133], v[98:113]
	ds_read_b128 v[82:85], v2 offset:128
	ds_read_b128 v[86:89], v2 offset:160
	s_waitcnt lgkmcnt(1)
	v_mfma_f32_32x32x16_bf16 v[98:113], v[82:85], v[126:129], v[98:113]
	s_waitcnt lgkmcnt(0)
	v_mfma_f32_32x32x16_bf16 v[98:113], v[86:89], v[122:125], v[98:113]
	ds_read_b128 v[82:85], v2 offset:192
	ds_read_b128 v[86:89], v2 offset:224
	s_waitcnt lgkmcnt(1)
	v_mfma_f32_32x32x16_bf16 v[98:113], v[82:85], v[118:121], v[98:113]
	ds_read_b128 v[82:85], v2 offset:8704
	ds_read_b128 v[192:195], v2 offset:8736
	s_waitcnt lgkmcnt(2)
	v_mfma_f32_32x32x16_bf16 v[98:113], v[86:89], v[114:117], v[98:113]
	s_waitcnt lgkmcnt(1)
	v_mfma_f32_32x32x16_bf16 v[82:97], v[82:85], v[142:145], 0
	s_waitcnt lgkmcnt(0)
	v_mfma_f32_32x32x16_bf16 v[82:97], v[192:195], v[138:141], v[82:97]
	ds_read_b128 v[192:195], v2 offset:8768
	ds_read_b128 v[196:199], v2 offset:8800
	s_waitcnt lgkmcnt(1)
	v_mfma_f32_32x32x16_bf16 v[82:97], v[192:195], v[134:137], v[82:97]
	s_waitcnt lgkmcnt(0)
	v_mfma_f32_32x32x16_bf16 v[82:97], v[196:199], v[130:133], v[82:97]
	ds_read_b128 v[192:195], v2 offset:8832
	ds_read_b128 v[196:199], v2 offset:8864
	s_waitcnt lgkmcnt(1)
	v_mfma_f32_32x32x16_bf16 v[82:97], v[192:195], v[126:129], v[82:97]
	s_waitcnt lgkmcnt(0)
	v_mfma_f32_32x32x16_bf16 v[82:97], v[196:199], v[122:125], v[82:97]
	ds_read_b128 v[192:195], v2 offset:8896
	ds_read_b128 v[196:199], v2 offset:8928
	v_max3_f32 v2, v98, v99, v100
	v_max3_f32 v2, v2, v101, v102
	v_max3_f32 v2, v2, v103, v104
	v_max3_f32 v2, v2, v105, v106
	v_max3_f32 v2, v2, v107, v108
	v_max3_f32 v2, v2, v109, v110
	s_waitcnt lgkmcnt(1)
	v_mfma_f32_32x32x16_bf16 v[82:97], v[192:195], v[118:121], v[82:97]
	v_max3_f32 v2, v2, v111, v112
	s_waitcnt lgkmcnt(0)
	v_mfma_f32_32x32x16_bf16 v[82:97], v[196:199], v[114:117], v[82:97]
	s_nop 11
	v_max_f32_e32 v16, v83, v83
	v_max_f32_e32 v17, v82, v82
	v_max_f32_e32 v16, v17, v16
	v_max3_f32 v16, v16, v84, v85
	v_max3_f32 v16, v16, v86, v87
	v_max3_f32 v16, v16, v88, v89
	v_max3_f32 v16, v16, v90, v91
	v_max3_f32 v16, v16, v92, v93
	v_max3_f32 v16, v16, v94, v95
	v_max3_f32 v16, v16, v96, v97
	v_max3_f32 v2, v2, v113, v16
	v_mov_b32_e32 v16, v2
	s_nop 1
	v_permlane32_swap_b32_e32 v2, v16
	v_max_f32_e32 v16, v16, v16
	v_max_f32_e32 v2, v2, v2
	v_max_f32_e32 v2, v2, v16
	v_add_f32_e32 v16, 0x41a00000, v158
	v_cmp_gt_f32_e32 vcc, v2, v16
	s_cbranch_vccz .LBB0_1319
	v_max_f32_e32 v2, v2, v2
	v_max_f32_e32 v16, v158, v158
	v_max_f32_e32 v16, v16, v2
	v_sub_f32_e32 v2, v158, v16
	v_exp_f32_e32 v2, v2
	v_mov_b32_e32 v158, v16
	v_pk_mul_f32 v[80:81], v[80:81], v[2:3] op_sel_hi:[1,0]
	v_pk_mul_f32 v[78:79], v[78:79], v[2:3] op_sel_hi:[1,0]
	v_pk_mul_f32 v[76:77], v[76:77], v[2:3] op_sel_hi:[1,0]
	v_pk_mul_f32 v[74:75], v[74:75], v[2:3] op_sel_hi:[1,0]
	v_pk_mul_f32 v[72:73], v[72:73], v[2:3] op_sel_hi:[1,0]
	v_pk_mul_f32 v[70:71], v[70:71], v[2:3] op_sel_hi:[1,0]
	v_pk_mul_f32 v[68:69], v[68:69], v[2:3] op_sel_hi:[1,0]
	v_pk_mul_f32 v[66:67], v[66:67], v[2:3] op_sel_hi:[1,0]
	v_pk_mul_f32 v[64:65], v[64:65], v[2:3] op_sel_hi:[1,0]
	v_pk_mul_f32 v[62:63], v[62:63], v[2:3] op_sel_hi:[1,0]
	v_pk_mul_f32 v[60:61], v[60:61], v[2:3] op_sel_hi:[1,0]
	v_pk_mul_f32 v[58:59], v[58:59], v[2:3] op_sel_hi:[1,0]
	v_pk_mul_f32 v[56:57], v[56:57], v[2:3] op_sel_hi:[1,0]
	v_pk_mul_f32 v[54:55], v[54:55], v[2:3] op_sel_hi:[1,0]
	v_pk_mul_f32 v[52:53], v[52:53], v[2:3] op_sel_hi:[1,0]
	v_pk_mul_f32 v[50:51], v[50:51], v[2:3] op_sel_hi:[1,0]
	v_pk_mul_f32 v[48:49], v[48:49], v[2:3] op_sel_hi:[1,0]
	v_pk_mul_f32 v[46:47], v[46:47], v[2:3] op_sel_hi:[1,0]
	v_pk_mul_f32 v[44:45], v[44:45], v[2:3] op_sel_hi:[1,0]
	v_pk_mul_f32 v[42:43], v[42:43], v[2:3] op_sel_hi:[1,0]
	v_pk_mul_f32 v[40:41], v[40:41], v[2:3] op_sel_hi:[1,0]
	v_pk_mul_f32 v[38:39], v[38:39], v[2:3] op_sel_hi:[1,0]
	v_pk_mul_f32 v[36:37], v[36:37], v[2:3] op_sel_hi:[1,0]
	v_pk_mul_f32 v[34:35], v[34:35], v[2:3] op_sel_hi:[1,0]
	v_pk_mul_f32 v[32:33], v[32:33], v[2:3] op_sel_hi:[1,0]
	v_pk_mul_f32 v[30:31], v[30:31], v[2:3] op_sel_hi:[1,0]
	v_pk_mul_f32 v[28:29], v[28:29], v[2:3] op_sel_hi:[1,0]
	v_pk_mul_f32 v[26:27], v[26:27], v[2:3] op_sel_hi:[1,0]
	v_pk_mul_f32 v[24:25], v[24:25], v[2:3] op_sel_hi:[1,0]
	v_pk_mul_f32 v[22:23], v[22:23], v[2:3] op_sel_hi:[1,0]
	v_pk_mul_f32 v[20:21], v[20:21], v[2:3] op_sel_hi:[1,0]
	v_pk_mul_f32 v[18:19], v[18:19], v[2:3] op_sel_hi:[1,0]
	v_mul_f32_e32 v153, v153, v2
	s_branch .LBB0_1319
